# mlstm_a3 epilogue: output-gate rows and gain vectors of all eight column groups loaded together (eight exposed round trips -> one)
# baseline (speedup 1.0000x reference)
.LBB0_943:
	s_or_b64 exec, exec, s[0:1]
	v_pk_add_f32 v[68:69], v[82:83], v[84:85]
	s_nop 0
	v_fmac_f32_e32 v68, v66, v69
	v_add_f32_e32 v66, v87, v127
	v_mul_f32_e32 v66, 0xbfb8aa3b, v66
	v_exp_f32_e32 v66, v66
	s_nop 0
	v_max_f32_e64 v66, |v68|, v66
	v_div_scale_f32 v68, s[0:1], v66, v66, 1.0
	v_rcp_f32_e32 v69, v68
	s_nop 0
	v_fma_f32 v82, -v68, v69, 1.0
	v_fmac_f32_e32 v69, v82, v69
	v_div_scale_f32 v82, vcc, 1.0, v66, 1.0
	v_mul_f32_e32 v83, v82, v69
	v_fma_f32 v84, -v68, v83, v82
	v_fmac_f32_e32 v83, v84, v69
	v_fma_f32 v68, -v68, v83, v82
	v_div_fmas_f32 v68, v68, v69, v83
	v_div_fixup_f32 v66, v68, v66, 1.0
	v_pk_fma_f32 v[90:91], v[28:29], v[66:67], 0 op_sel_hi:[1,0,0]
	v_pk_fma_f32 v[28:29], v[30:31], v[66:67], 0 op_sel_hi:[1,0,0]
	v_pk_fma_f32 v[30:31], v[34:35], v[66:67], 0 op_sel_hi:[1,0,0]
	v_pk_fma_f32 v[34:35], v[36:37], v[66:67], 0 op_sel_hi:[1,0,0]
	v_lshl_add_u32 v36, v128, 2, 0
	v_pk_fma_f32 v[82:83], v[22:23], v[66:67], 0 op_sel_hi:[1,0,0]
	v_pk_fma_f32 v[22:23], v[48:49], v[66:67], 0 op_sel_hi:[1,0,0]
	v_add_u32_e32 v48, 0x1be00, v36
	v_pk_fma_f32 v[68:69], v[18:19], v[66:67], 0 op_sel_hi:[1,0,0]
	v_pk_fma_f32 v[86:87], v[20:21], v[66:67], 0 op_sel_hi:[1,0,0]
	v_pk_fma_f32 v[88:89], v[24:25], v[66:67], 0 op_sel_hi:[1,0,0]
	v_pk_fma_f32 v[84:85], v[26:27], v[66:67], 0 op_sel_hi:[1,0,0]
	v_pk_fma_f32 v[92:93], v[32:33], v[66:67], 0 op_sel_hi:[1,0,0]
	v_pk_fma_f32 v[24:25], v[38:39], v[66:67], 0 op_sel_hi:[1,0,0]
	v_pk_fma_f32 v[32:33], v[40:41], v[66:67], 0 op_sel_hi:[1,0,0]
	v_pk_fma_f32 v[20:21], v[42:43], v[66:67], 0 op_sel_hi:[1,0,0]
	v_pk_fma_f32 v[26:27], v[44:45], v[66:67], 0 op_sel_hi:[1,0,0]
	v_pk_fma_f32 v[18:19], v[46:47], v[66:67], 0 op_sel_hi:[1,0,0]
	ds_read_b128 v[36:39], v48
	ds_read_b128 v[40:43], v48 offset:16
	ds_read_b128 v[44:47], v48 offset:32
	ds_read_b128 v[100:103], v48 offset:48
	s_waitcnt lgkmcnt(3)
	v_fma_f32 v49, v36, v107, 0
	v_fmac_f32_e32 v49, v37, v108
	v_fmac_f32_e32 v49, v38, v109
	v_fmac_f32_e32 v49, v39, v110
	s_waitcnt lgkmcnt(2)
	v_fmac_f32_e32 v49, v40, v111
	v_fmac_f32_e32 v49, v41, v112
	v_fmac_f32_e32 v49, v42, v113
	v_fmac_f32_e32 v49, v43, v118
	s_waitcnt lgkmcnt(1)
	v_fmac_f32_e32 v49, v44, v119
	v_fmac_f32_e32 v49, v45, v120
	v_fmac_f32_e32 v49, v46, v121
	v_fmac_f32_e32 v49, v47, v122
	ds_read_b128 v[36:39], v48 offset:64
	s_waitcnt lgkmcnt(1)
	v_fmac_f32_e32 v49, v100, v123
	v_fmac_f32_e32 v49, v101, v124
	v_fmac_f32_e32 v49, v102, v125
	v_fmac_f32_e32 v49, v103, v126
	s_waitcnt lgkmcnt(0)
	v_fmac_f32_e32 v49, v36, v114
	v_fmac_f32_e32 v49, v37, v115
	v_fmac_f32_e32 v49, v38, v116
	v_fmac_f32_e32 v49, v39, v117
	ds_read_b128 v[36:39], v48 offset:80
	s_waitcnt lgkmcnt(0)
	v_pk_mul_f32 v[36:37], v[36:37], v[78:79]
	s_nop 0
	v_add_f32_e32 v36, v49, v36
	v_add_f32_e32 v40, v36, v37
	v_pk_mul_f32 v[36:37], v[38:39], v[80:81]
	s_nop 0
	v_add_f32_e32 v36, v40, v36
	v_add_f32_e32 v40, v36, v37
	ds_read_b128 v[36:39], v48 offset:96
	s_waitcnt lgkmcnt(0)
	v_pk_mul_f32 v[36:37], v[36:37], v[74:75]
	s_nop 0
	v_add_f32_e32 v36, v40, v36
	v_add_f32_e32 v40, v36, v37
	v_pk_mul_f32 v[36:37], v[38:39], v[76:77]
	s_nop 0
	v_add_f32_e32 v36, v40, v36
	v_add_f32_e32 v40, v36, v37
	ds_read_b128 v[36:39], v48 offset:112
	s_waitcnt lgkmcnt(0)
	v_pk_mul_f32 v[36:37], v[36:37], v[70:71]
	s_nop 0
	v_add_f32_e32 v36, v40, v36
	v_add_f32_e32 v40, v36, v37
	v_pk_mul_f32 v[36:37], v[38:39], v[72:73]
	s_nop 0
	v_add_f32_e32 v36, v40, v36
	v_add_f32_e32 v66, v36, v37
	ds_bpermute_b32 v36, v97, v66
	ds_bpermute_b32 v37, v97, v67
	s_waitcnt lgkmcnt(0)
	v_pk_add_f32 v[36:37], v[66:67], v[36:37]
	ds_bpermute_b32 v38, v98, v36
	ds_bpermute_b32 v39, v98, v37
	s_waitcnt lgkmcnt(0)
	v_pk_add_f32 v[36:37], v[36:37], v[38:39]
	s_nop 0
	v_fmac_f32_e32 v37, v0, v36
	v_add_u32_e32 v0, 0x1bc00, v106
	ds_read_b32 v0, v0
	s_waitcnt lgkmcnt(0)
	v_add_f32_e32 v0, v105, v0
	v_mul_f32_e32 v0, 0xbfb8aa3b, v0
	v_exp_f32_e32 v0, v0
	s_nop 0
	v_max_f32_e64 v0, |v37|, v0
	v_div_scale_f32 v36, s[0:1], v0, v0, 1.0
	v_rcp_f32_e32 v37, v36
	s_nop 0
	v_fma_f32 v38, -v36, v37, 1.0
	v_fmac_f32_e32 v37, v38, v37
	v_div_scale_f32 v38, vcc, 1.0, v0, 1.0
	v_mul_f32_e32 v39, v38, v37
	v_fma_f32 v40, -v36, v39, v38
	v_fmac_f32_e32 v39, v40, v37
	v_fma_f32 v36, -v36, v39, v38
	v_div_fmas_f32 v36, v36, v37, v39
	v_div_fixup_f32 v0, v36, v0, 1.0
	v_pk_fma_f32 v[2:3], v[2:3], v[0:1], v[68:69] op_sel_hi:[1,0,1]
	v_pk_fma_f32 v[4:5], v[4:5], v[0:1], v[86:87] op_sel_hi:[1,0,1]
	v_pk_fma_f32 v[8:9], v[8:9], v[0:1], v[88:89] op_sel_hi:[1,0,1]
	v_pk_fma_f32 v[6:7], v[6:7], v[0:1], v[82:83] op_sel_hi:[1,0,1]
	v_pk_fma_f32 v[12:13], v[12:13], v[0:1], v[90:91] op_sel_hi:[1,0,1]
	v_pk_fma_f32 v[10:11], v[10:11], v[0:1], v[84:85] op_sel_hi:[1,0,1]
	v_pk_fma_f32 v[16:17], v[16:17], v[0:1], v[92:93] op_sel_hi:[1,0,1]
	v_pk_fma_f32 v[14:15], v[14:15], v[0:1], v[28:29] op_sel_hi:[1,0,1]
	v_pk_fma_f32 v[36:37], v[52:53], v[0:1], v[34:35] op_sel_hi:[1,0,1]
	v_pk_fma_f32 v[38:39], v[50:51], v[0:1], v[30:31] op_sel_hi:[1,0,1]
	v_pk_fma_f32 v[40:41], v[56:57], v[0:1], v[32:33] op_sel_hi:[1,0,1]
	v_pk_fma_f32 v[42:43], v[54:55], v[0:1], v[24:25] op_sel_hi:[1,0,1]
	v_pk_fma_f32 v[44:45], v[60:61], v[0:1], v[26:27] op_sel_hi:[1,0,1]
	v_pk_fma_f32 v[46:47], v[58:59], v[0:1], v[20:21] op_sel_hi:[1,0,1]
	v_pk_fma_f32 v[48:49], v[64:65], v[0:1], v[22:23] op_sel_hi:[1,0,1]
	v_pk_fma_f32 v[50:51], v[62:63], v[0:1], v[18:19] op_sel_hi:[1,0,1]
	v_add_f32_e32 v0, v2, v3
	v_add_f32_e32 v0, v4, v0
	v_add_f32_e32 v0, v5, v0
	v_add_f32_e32 v0, v6, v0
	v_add_f32_e32 v0, v7, v0
	v_add_f32_e32 v0, v8, v0
	v_add_f32_e32 v0, v9, v0
	v_add_f32_e32 v0, v10, v0
	v_add_f32_e32 v0, v11, v0
	v_add_f32_e32 v0, v12, v0
	v_add_f32_e32 v0, v13, v0
	v_add_f32_e32 v0, v14, v0
	v_add_f32_e32 v0, v15, v0
	v_add_f32_e32 v0, v16, v0
	v_add_f32_e32 v0, v17, v0
	v_add_f32_e32 v0, v38, v0
	v_add_f32_e32 v0, v39, v0
	v_add_f32_e32 v0, v36, v0
	v_add_f32_e32 v0, v37, v0
	v_add_f32_e32 v0, v42, v0
	v_add_f32_e32 v0, v43, v0
	v_add_f32_e32 v0, v40, v0
	v_add_f32_e32 v0, v41, v0
	v_add_f32_e32 v0, v46, v0
	v_add_f32_e32 v0, v47, v0
	v_add_f32_e32 v0, v44, v0
	v_add_f32_e32 v0, v45, v0
	v_add_f32_e32 v0, v50, v0
	v_add_f32_e32 v0, v51, v0
	v_add_f32_e32 v0, v48, v0
	v_add_f32_e32 v0, v49, v0
	ds_bpermute_b32 v18, v97, v0
	s_andn2_b64 vcc, exec, s[36:37]
	s_waitcnt lgkmcnt(0)
	v_add_f32_e32 v0, v0, v18
	ds_bpermute_b32 v18, v98, v0
	s_waitcnt lgkmcnt(0)
	v_add_f32_e32 v0, v0, v18
	v_mul_f32_e32 v0, 0x3c000000, v0
	v_pk_add_f32 v[32:33], v[2:3], v[0:1] op_sel_hi:[1,0] neg_lo:[0,1] neg_hi:[0,1]
	v_pk_add_f32 v[34:35], v[4:5], v[0:1] op_sel_hi:[1,0] neg_lo:[0,1] neg_hi:[0,1]
	v_pk_mul_f32 v[52:53], v[32:33], v[32:33]
	v_pk_mul_f32 v[54:55], v[34:35], v[34:35]
	v_pk_add_f32 v[2:3], v[6:7], v[0:1] op_sel_hi:[1,0] neg_lo:[0,1] neg_hi:[0,1]
	v_pk_add_f32 v[4:5], v[8:9], v[0:1] op_sel_hi:[1,0] neg_lo:[0,1] neg_hi:[0,1]
	v_pk_add_f32 v[28:29], v[10:11], v[0:1] op_sel_hi:[1,0] neg_lo:[0,1] neg_hi:[0,1]
	v_pk_add_f32 v[30:31], v[12:13], v[0:1] op_sel_hi:[1,0] neg_lo:[0,1] neg_hi:[0,1]
	v_pk_add_f32 v[24:25], v[14:15], v[0:1] op_sel_hi:[1,0] neg_lo:[0,1] neg_hi:[0,1]
	v_pk_add_f32 v[26:27], v[16:17], v[0:1] op_sel_hi:[1,0] neg_lo:[0,1] neg_hi:[0,1]
	v_pk_add_f32 v[20:21], v[38:39], v[0:1] op_sel_hi:[1,0] neg_lo:[0,1] neg_hi:[0,1]
	v_pk_add_f32 v[22:23], v[36:37], v[0:1] op_sel_hi:[1,0] neg_lo:[0,1] neg_hi:[0,1]
	v_pk_add_f32 v[16:17], v[42:43], v[0:1] op_sel_hi:[1,0] neg_lo:[0,1] neg_hi:[0,1]
	v_pk_add_f32 v[18:19], v[40:41], v[0:1] op_sel_hi:[1,0] neg_lo:[0,1] neg_hi:[0,1]
	v_pk_add_f32 v[12:13], v[46:47], v[0:1] op_sel_hi:[1,0] neg_lo:[0,1] neg_hi:[0,1]
	v_pk_add_f32 v[14:15], v[44:45], v[0:1] op_sel_hi:[1,0] neg_lo:[0,1] neg_hi:[0,1]
	v_pk_add_f32 v[10:11], v[50:51], v[0:1] op_sel_hi:[1,0] neg_lo:[0,1] neg_hi:[0,1]
	v_pk_add_f32 v[6:7], v[48:49], v[0:1] op_sel_hi:[1,0] neg_lo:[0,1] neg_hi:[0,1]
	v_add_f32_e32 v0, v52, v53
	v_add_f32_e32 v0, v54, v0
	v_pk_mul_f32 v[56:57], v[2:3], v[2:3]
	v_add_f32_e32 v0, v55, v0
	v_add_f32_e32 v0, v56, v0
	v_pk_mul_f32 v[8:9], v[4:5], v[4:5]
	v_add_f32_e32 v0, v57, v0
	v_add_f32_e32 v0, v8, v0
	v_pk_mul_f32 v[58:59], v[28:29], v[28:29]
	v_add_f32_e32 v0, v9, v0
	v_add_f32_e32 v0, v58, v0
	v_pk_mul_f32 v[60:61], v[30:31], v[30:31]
	v_add_f32_e32 v0, v59, v0
	v_add_f32_e32 v0, v60, v0
	v_pk_mul_f32 v[62:63], v[24:25], v[24:25]
	v_add_f32_e32 v0, v61, v0
	v_add_f32_e32 v0, v62, v0
	v_pk_mul_f32 v[64:65], v[26:27], v[26:27]
	v_add_f32_e32 v0, v63, v0
	v_add_f32_e32 v0, v64, v0
	v_pk_mul_f32 v[38:39], v[20:21], v[20:21]
	v_add_f32_e32 v0, v65, v0
	v_add_f32_e32 v0, v38, v0
	v_pk_mul_f32 v[36:37], v[22:23], v[22:23]
	v_add_f32_e32 v0, v39, v0
	v_add_f32_e32 v0, v36, v0
	v_pk_mul_f32 v[42:43], v[16:17], v[16:17]
	v_add_f32_e32 v0, v37, v0
	v_add_f32_e32 v0, v42, v0
	v_pk_mul_f32 v[40:41], v[18:19], v[18:19]
	v_add_f32_e32 v0, v43, v0
	v_add_f32_e32 v0, v40, v0
	v_pk_mul_f32 v[46:47], v[12:13], v[12:13]
	v_add_f32_e32 v0, v41, v0
	v_add_f32_e32 v0, v46, v0
	v_pk_mul_f32 v[44:45], v[14:15], v[14:15]
	v_add_f32_e32 v0, v47, v0
	v_add_f32_e32 v0, v44, v0
	v_pk_mul_f32 v[50:51], v[10:11], v[10:11]
	v_add_f32_e32 v0, v45, v0
	v_add_f32_e32 v0, v50, v0
	v_pk_mul_f32 v[48:49], v[6:7], v[6:7]
	v_add_f32_e32 v0, v51, v0
	v_add_f32_e32 v0, v48, v0
	v_add_f32_e32 v0, v49, v0
	ds_bpermute_b32 v8, v97, v0
	s_waitcnt lgkmcnt(0)
	v_add_f32_e32 v37, v0, v8
	ds_bpermute_b32 v38, v98, v37
	s_cbranch_vccnz .LBB0_724
	v_add_u32_e32 v0, s86, v96
	v_or_b32_e32 v0, v0, v94
	v_mov_b64_e32 v[8:9], s[50:51]
	v_mad_i64_i32 v[8:9], s[0:1], v0, s65, v[8:9]
	v_lshl_add_u64 v[8:9], v[8:9], 0, s[8:9]
	v_lshlrev_b32_e32 v0, 1, v95
	v_lshl_add_u64 v[8:9], v[8:9], 0, v[0:1]
	global_load_dwordx2 v[44:45], v[8:9], off offset:3072
	global_load_dwordx2 v[46:47], v[8:9], off offset:3104
	s_add_u32 s0, s23, s87
	v_lshlrev_b32_e32 v36, 2, v95
	s_addc_u32 s1, s17, 0
	global_load_dwordx4 v[40:43], v36, s[0:1]
	global_load_dwordx4 v[166:169], v36, s[0:1] offset:64
	global_load_dwordx4 v[170:173], v36, s[0:1] offset:128
	global_load_dwordx4 v[174:177], v36, s[0:1] offset:192
	global_load_dwordx4 v[178:181], v36, s[0:1] offset:256
	global_load_dwordx4 v[182:185], v36, s[0:1] offset:320
	global_load_dwordx4 v[186:189], v36, s[0:1] offset:384
	global_load_dwordx4 v[108:111], v36, s[0:1] offset:448
	global_load_dwordx2 v[96:97], v[8:9], off offset:3136
	global_load_dwordx2 v[98:99], v[8:9], off offset:3168
	global_load_dwordx2 v[100:101], v[8:9], off offset:3200
	global_load_dwordx2 v[102:103], v[8:9], off offset:3232
	global_load_dwordx2 v[104:105], v[8:9], off offset:3264
	global_load_dwordx2 v[106:107], v[8:9], off offset:3296
	s_waitcnt lgkmcnt(0)
	v_add_f32_e32 v0, v37, v38
	v_fmamk_f32 v0, v0, 0x3c000000, v194
	v_cmp_gt_f32_e32 vcc, s76, v0
	v_mul_f32_e32 v37, 0x4b800000, v0
	s_waitcnt vmcnt(2)
	v_and_b32_e32 v38, 0xffff0000, v44
	v_cndmask_b32_e32 v0, v0, v37, vcc
	v_rsq_f32_e32 v0, v0
	v_lshlrev_b32_e32 v39, 16, v45
	v_mul_f32_e32 v38, 0xbfb8aa3b, v38
	v_mul_f32_e32 v39, 0xbfb8aa3b, v39
	v_mul_f32_e32 v37, 0x45800000, v0
	v_cndmask_b32_e32 v0, v0, v37, vcc
	v_lshlrev_b32_e32 v37, 16, v44
	v_and_b32_e32 v44, 0xffff0000, v45
	v_mul_f32_e32 v37, 0xbfb8aa3b, v37
	v_mul_f32_e32 v44, 0xbfb8aa3b, v44
	v_exp_f32_e32 v37, v37
	v_exp_f32_e32 v38, v38
	v_exp_f32_e32 v39, v39
	v_exp_f32_e32 v44, v44
	v_add_f32_e32 v37, 1.0, v37
	v_add_f32_e32 v45, 1.0, v38
	v_add_f32_e32 v48, 1.0, v39
	v_add_f32_e32 v49, 1.0, v44
	v_rcp_f32_e32 v38, v37
	v_rcp_f32_e32 v39, v45
	v_rcp_f32_e32 v44, v48
	v_rcp_f32_e32 v45, v49
	v_pk_mul_f32 v[32:33], v[32:33], v[0:1] op_sel_hi:[1,0]
	v_pk_mul_f32 v[34:35], v[34:35], v[0:1] op_sel_hi:[1,0]
	s_waitcnt vmcnt(0)
	v_pk_mul_f32 v[32:33], v[32:33], v[40:41]
	v_pk_mul_f32 v[34:35], v[34:35], v[42:43]
	v_pk_mul_f32 v[32:33], v[32:33], v[38:39]
	v_pk_mul_f32 v[34:35], v[34:35], v[44:45]
	v_cvt_pk_bf16_f32 v32, v32, v33
	v_cvt_pk_bf16_f32 v33, v34, v35
	global_store_dwordx2 v[8:9], v[32:33], off offset:3072
	s_nop 1
	v_mov_b64_e32 v[38:39], v[166:167]
	v_mov_b64_e32 v[40:41], v[168:169]
	s_nop 1
	v_mov_b64_e32 v[34:35], v[96:97]
	v_lshlrev_b32_e32 v32, 16, v46
	v_and_b32_e32 v33, 0xffff0000, v46
	v_lshlrev_b32_e32 v37, 16, v47
	v_and_b32_e32 v42, 0xffff0000, v47
	v_mul_f32_e32 v32, 0xbfb8aa3b, v32
	v_mul_f32_e32 v33, 0xbfb8aa3b, v33
	v_mul_f32_e32 v37, 0xbfb8aa3b, v37
	v_mul_f32_e32 v42, 0xbfb8aa3b, v42
	v_exp_f32_e32 v32, v32
	v_exp_f32_e32 v33, v33
	v_exp_f32_e32 v37, v37
	v_exp_f32_e32 v42, v42
	v_add_f32_e32 v32, 1.0, v32
	v_add_f32_e32 v33, 1.0, v33
	v_add_f32_e32 v37, 1.0, v37
	v_add_f32_e32 v43, 1.0, v42
	v_rcp_f32_e32 v32, v32
	v_rcp_f32_e32 v33, v33
	v_rcp_f32_e32 v42, v37
	v_rcp_f32_e32 v43, v43
	v_pk_mul_f32 v[2:3], v[2:3], v[0:1] op_sel_hi:[1,0]
	v_pk_mul_f32 v[4:5], v[4:5], v[0:1] op_sel_hi:[1,0]
	v_pk_mul_f32 v[28:29], v[28:29], v[0:1] op_sel_hi:[1,0]
	v_pk_mul_f32 v[30:31], v[30:31], v[0:1] op_sel_hi:[1,0]
	v_pk_mul_f32 v[24:25], v[24:25], v[0:1] op_sel_hi:[1,0]
	v_pk_mul_f32 v[26:27], v[26:27], v[0:1] op_sel_hi:[1,0]
	v_pk_mul_f32 v[20:21], v[20:21], v[0:1] op_sel_hi:[1,0]
	v_pk_mul_f32 v[22:23], v[22:23], v[0:1] op_sel_hi:[1,0]
	v_pk_mul_f32 v[16:17], v[16:17], v[0:1] op_sel_hi:[1,0]
	v_pk_mul_f32 v[18:19], v[18:19], v[0:1] op_sel_hi:[1,0]
	v_pk_mul_f32 v[12:13], v[12:13], v[0:1] op_sel_hi:[1,0]
	v_pk_mul_f32 v[14:15], v[14:15], v[0:1] op_sel_hi:[1,0]
	v_pk_mul_f32 v[10:11], v[10:11], v[0:1] op_sel_hi:[1,0]
	v_pk_mul_f32 v[6:7], v[6:7], v[0:1] op_sel_hi:[1,0]
	s_waitcnt vmcnt(1)
	v_pk_mul_f32 v[2:3], v[2:3], v[38:39]
	v_pk_mul_f32 v[4:5], v[4:5], v[40:41]
	v_pk_mul_f32 v[2:3], v[2:3], v[32:33]
	v_pk_mul_f32 v[4:5], v[4:5], v[42:43]
	v_cvt_pk_bf16_f32 v2, v2, v3
	v_cvt_pk_bf16_f32 v3, v4, v5
	global_store_dwordx2 v[8:9], v[2:3], off offset:3104
	s_nop 1
	v_mov_b64_e32 v[2:3], v[170:171]
	v_mov_b64_e32 v[4:5], v[172:173]
	s_nop 0
	s_nop 1
	v_mov_b64_e32 v[32:33], v[98:99]
	s_waitcnt vmcnt(3)
	v_lshlrev_b32_e32 v37, 16, v34
	v_and_b32_e32 v34, 0xffff0000, v34
	v_lshlrev_b32_e32 v38, 16, v35
	v_and_b32_e32 v35, 0xffff0000, v35
	v_mul_f32_e32 v37, 0xbfb8aa3b, v37
	v_mul_f32_e32 v34, 0xbfb8aa3b, v34
	v_mul_f32_e32 v38, 0xbfb8aa3b, v38
	v_mul_f32_e32 v35, 0xbfb8aa3b, v35
	v_exp_f32_e32 v37, v37
	v_exp_f32_e32 v34, v34
	v_exp_f32_e32 v38, v38
	v_exp_f32_e32 v35, v35
	v_add_f32_e32 v37, 1.0, v37
	v_add_f32_e32 v39, 1.0, v34
	v_add_f32_e32 v38, 1.0, v38
	v_add_f32_e32 v40, 1.0, v35
	v_rcp_f32_e32 v34, v37
	v_rcp_f32_e32 v35, v39
	v_rcp_f32_e32 v38, v38
	v_rcp_f32_e32 v39, v40
	s_waitcnt vmcnt(1)
	v_pk_mul_f32 v[2:3], v[28:29], v[2:3]
	v_pk_mul_f32 v[4:5], v[30:31], v[4:5]
	v_pk_mul_f32 v[2:3], v[2:3], v[34:35]
	v_pk_mul_f32 v[4:5], v[4:5], v[38:39]
	v_cvt_pk_bf16_f32 v2, v2, v3
	v_cvt_pk_bf16_f32 v3, v4, v5
	global_store_dwordx2 v[8:9], v[2:3], off offset:3136
	s_nop 1
	v_mov_b64_e32 v[2:3], v[174:175]
	v_mov_b64_e32 v[4:5], v[176:177]
	s_nop 0
	s_nop 1
	v_mov_b64_e32 v[28:29], v[100:101]
	s_waitcnt vmcnt(3)
	v_lshlrev_b32_e32 v30, 16, v32
	v_and_b32_e32 v31, 0xffff0000, v32
	v_lshlrev_b32_e32 v32, 16, v33
	v_and_b32_e32 v33, 0xffff0000, v33
	v_mul_f32_e32 v30, 0xbfb8aa3b, v30
	v_mul_f32_e32 v31, 0xbfb8aa3b, v31
	v_mul_f32_e32 v32, 0xbfb8aa3b, v32
	v_mul_f32_e32 v33, 0xbfb8aa3b, v33
	v_exp_f32_e32 v30, v30
	v_exp_f32_e32 v31, v31
	v_exp_f32_e32 v32, v32
	v_exp_f32_e32 v33, v33
	v_add_f32_e32 v30, 1.0, v30
	v_add_f32_e32 v31, 1.0, v31
	v_add_f32_e32 v32, 1.0, v32
	v_add_f32_e32 v33, 1.0, v33
	v_rcp_f32_e32 v30, v30
	v_rcp_f32_e32 v31, v31
	v_rcp_f32_e32 v32, v32
	v_rcp_f32_e32 v33, v33
	s_waitcnt vmcnt(1)
	v_pk_mul_f32 v[2:3], v[24:25], v[2:3]
	v_pk_mul_f32 v[4:5], v[26:27], v[4:5]
	v_pk_mul_f32 v[2:3], v[2:3], v[30:31]
	v_pk_mul_f32 v[4:5], v[4:5], v[32:33]
	v_cvt_pk_bf16_f32 v2, v2, v3
	v_cvt_pk_bf16_f32 v3, v4, v5
	global_store_dwordx2 v[8:9], v[2:3], off offset:3168
	s_nop 1
	v_mov_b64_e32 v[2:3], v[178:179]
	v_mov_b64_e32 v[4:5], v[180:181]
	s_nop 0
	s_nop 1
	v_mov_b64_e32 v[24:25], v[102:103]
	s_waitcnt vmcnt(3)
	v_lshlrev_b32_e32 v26, 16, v28
	v_and_b32_e32 v27, 0xffff0000, v28
	v_lshlrev_b32_e32 v28, 16, v29
	v_and_b32_e32 v29, 0xffff0000, v29
	v_mul_f32_e32 v26, 0xbfb8aa3b, v26
	v_mul_f32_e32 v27, 0xbfb8aa3b, v27
	v_mul_f32_e32 v28, 0xbfb8aa3b, v28
	v_mul_f32_e32 v29, 0xbfb8aa3b, v29
	v_exp_f32_e32 v26, v26
	v_exp_f32_e32 v27, v27
	v_exp_f32_e32 v28, v28
	v_exp_f32_e32 v29, v29
	v_add_f32_e32 v26, 1.0, v26
	v_add_f32_e32 v27, 1.0, v27
	v_add_f32_e32 v28, 1.0, v28
	v_add_f32_e32 v29, 1.0, v29
	v_rcp_f32_e32 v26, v26
	v_rcp_f32_e32 v27, v27
	v_rcp_f32_e32 v28, v28
	v_rcp_f32_e32 v29, v29
	s_waitcnt vmcnt(1)
	v_pk_mul_f32 v[2:3], v[20:21], v[2:3]
	v_pk_mul_f32 v[4:5], v[22:23], v[4:5]
	v_pk_mul_f32 v[2:3], v[2:3], v[26:27]
	v_pk_mul_f32 v[4:5], v[4:5], v[28:29]
	v_cvt_pk_bf16_f32 v2, v2, v3
	v_cvt_pk_bf16_f32 v3, v4, v5
	global_store_dwordx2 v[8:9], v[2:3], off offset:3200
	s_nop 1
	v_mov_b64_e32 v[2:3], v[182:183]
	v_mov_b64_e32 v[4:5], v[184:185]
	s_nop 0
	s_nop 1
	v_mov_b64_e32 v[20:21], v[104:105]
	s_waitcnt vmcnt(3)
	v_lshlrev_b32_e32 v22, 16, v24
	v_and_b32_e32 v23, 0xffff0000, v24
	v_lshlrev_b32_e32 v24, 16, v25
	v_and_b32_e32 v25, 0xffff0000, v25
	v_mul_f32_e32 v22, 0xbfb8aa3b, v22
	v_mul_f32_e32 v23, 0xbfb8aa3b, v23
	v_mul_f32_e32 v24, 0xbfb8aa3b, v24
	v_mul_f32_e32 v25, 0xbfb8aa3b, v25
	v_exp_f32_e32 v22, v22
	v_exp_f32_e32 v23, v23
	v_exp_f32_e32 v24, v24
	v_exp_f32_e32 v25, v25
	v_add_f32_e32 v22, 1.0, v22
	v_add_f32_e32 v23, 1.0, v23
	v_add_f32_e32 v24, 1.0, v24
	v_add_f32_e32 v25, 1.0, v25
	v_rcp_f32_e32 v22, v22
	v_rcp_f32_e32 v23, v23
	v_rcp_f32_e32 v24, v24
	v_rcp_f32_e32 v25, v25
	s_waitcnt vmcnt(1)
	v_pk_mul_f32 v[2:3], v[16:17], v[2:3]
	v_pk_mul_f32 v[4:5], v[18:19], v[4:5]
	v_pk_mul_f32 v[2:3], v[2:3], v[22:23]
	v_pk_mul_f32 v[4:5], v[4:5], v[24:25]
	v_cvt_pk_bf16_f32 v2, v2, v3
	v_cvt_pk_bf16_f32 v3, v4, v5
	global_store_dwordx2 v[8:9], v[2:3], off offset:3232
	s_nop 1
	v_mov_b64_e32 v[2:3], v[186:187]
	v_mov_b64_e32 v[4:5], v[188:189]
	s_nop 0
	s_nop 1
	v_mov_b64_e32 v[16:17], v[106:107]
	s_waitcnt vmcnt(3)
	v_lshlrev_b32_e32 v18, 16, v20
	v_and_b32_e32 v19, 0xffff0000, v20
	v_lshlrev_b32_e32 v20, 16, v21
	v_and_b32_e32 v21, 0xffff0000, v21
	v_mul_f32_e32 v18, 0xbfb8aa3b, v18
	v_mul_f32_e32 v19, 0xbfb8aa3b, v19
	v_mul_f32_e32 v20, 0xbfb8aa3b, v20
	v_mul_f32_e32 v21, 0xbfb8aa3b, v21
	v_exp_f32_e32 v18, v18
	v_exp_f32_e32 v19, v19
	v_exp_f32_e32 v20, v20
	v_exp_f32_e32 v21, v21
	v_add_f32_e32 v18, 1.0, v18
	v_add_f32_e32 v19, 1.0, v19
	v_add_f32_e32 v20, 1.0, v20
	v_add_f32_e32 v21, 1.0, v21
	v_rcp_f32_e32 v18, v18
	v_rcp_f32_e32 v19, v19
	v_rcp_f32_e32 v20, v20
	v_rcp_f32_e32 v21, v21
	s_waitcnt vmcnt(1)
	v_pk_mul_f32 v[2:3], v[12:13], v[2:3]
	v_pk_mul_f32 v[4:5], v[14:15], v[4:5]
	v_pk_mul_f32 v[2:3], v[2:3], v[18:19]
	v_pk_mul_f32 v[4:5], v[4:5], v[20:21]
	v_cvt_pk_bf16_f32 v2, v2, v3
	v_cvt_pk_bf16_f32 v3, v4, v5
	global_store_dwordx2 v[8:9], v[2:3], off offset:3264
	s_nop 1
	v_mov_b64_e32 v[2:3], v[108:109]
	v_mov_b64_e32 v[4:5], v[110:111]
	s_waitcnt vmcnt(2)
	v_lshlrev_b32_e32 v0, 16, v16
	v_and_b32_e32 v12, 0xffff0000, v16
	v_lshlrev_b32_e32 v13, 16, v17
	v_and_b32_e32 v14, 0xffff0000, v17
	v_mul_f32_e32 v0, 0xbfb8aa3b, v0
	v_mul_f32_e32 v12, 0xbfb8aa3b, v12
	v_mul_f32_e32 v13, 0xbfb8aa3b, v13
	v_mul_f32_e32 v14, 0xbfb8aa3b, v14
	v_exp_f32_e32 v0, v0
	v_exp_f32_e32 v12, v12
	v_exp_f32_e32 v13, v13
	v_exp_f32_e32 v14, v14
	v_add_f32_e32 v0, 1.0, v0
	v_add_f32_e32 v15, 1.0, v12
	v_add_f32_e32 v16, 1.0, v13
	v_add_f32_e32 v17, 1.0, v14
	v_rcp_f32_e32 v12, v0
	v_rcp_f32_e32 v13, v15
	v_rcp_f32_e32 v14, v16
	v_rcp_f32_e32 v15, v17
	s_waitcnt vmcnt(0)
	v_pk_mul_f32 v[2:3], v[10:11], v[2:3]
	v_pk_mul_f32 v[4:5], v[6:7], v[4:5]
	v_pk_mul_f32 v[2:3], v[2:3], v[12:13]
	v_pk_mul_f32 v[4:5], v[4:5], v[14:15]
	v_cvt_pk_bf16_f32 v2, v2, v3
	v_cvt_pk_bf16_f32 v3, v4, v5
	global_store_dwordx2 v[8:9], v[2:3], off offset:3296
	s_branch .LBB0_724
